# window size 8 items per WG (3424 deferred)
# baseline (speedup 1.0000x reference)
; __device__ __forceinline__ unsigned cvt_pk_bf16(float lo, float hi) { unsigned r; asm volatile("v_cvt_pk_bf16_f32 %0, %1, %2" : "=v"(r) : "v"(lo), "v"(hi)); return r; }
; #define LAS __attribute__((address_space(3)))
; __device__ __forceinline__ void tr_item_cu(const float* __restrict__ W, int K, int N, bf16* __restrict__ WT, const float* rowgain, int mode, LAS unsigned char* buf, int item, int wave, int lane) {
;     const int nblk = N >> 7, kb = item / nblk, nb = item - kb * nblk, k0 = 256 * kb, n0 = 128 * nb;
;     const int hr = lane >> 5, c = lane & 31, kw = 32 * wave + 16 * hr;
;     f32x4 v[16];
;     const float* src = W + (size_t)(k0 + kw) * N + n0 + 4 * c;
; #pragma unroll
;     for (int j = 0; j < 16; ++j) v[j] = __builtin_nontemporal_load((const f32x4*)(src + (size_t)j * N));
;     if (rowgain) {
; #pragma unroll
;         for (int q = 0; q < 4; ++q) { const f32x4 r4 = *(const f32x4*)(rowgain + k0 + kw + 4 * q);
; #pragma unroll
;             for (int e = 0; e < 4; ++e) v[4 * q + e] = v[4 * q + e] * r4[e]; }
;     }
; #pragma unroll
;     for (int i = 0; i < 4; ++i) {
;         u32x4 lo, hi;
;         lo.x = pg8::cvt_pk_bf16(v[0][i], v[1][i]);   lo.y = pg8::cvt_pk_bf16(v[2][i], v[3][i]);   lo.z = pg8::cvt_pk_bf16(v[4][i], v[5][i]);   lo.w = pg8::cvt_pk_bf16(v[6][i], v[7][i]);
;         hi.x = pg8::cvt_pk_bf16(v[8][i], v[9][i]);   hi.y = pg8::cvt_pk_bf16(v[10][i], v[11][i]); hi.z = pg8::cvt_pk_bf16(v[12][i], v[13][i]); hi.w = pg8::cvt_pk_bf16(v[14][i], v[15][i]);
;         LAS unsigned char* p = buf + (4 * c + i) * TCP + kw * 2;
;         *(LAS u32x4*)p = lo; *(LAS u32x4*)(p + 16) = hi;
;     }
;     __syncthreads();
; #pragma unroll
;     for (int m = 0; m < 8; ++m) { const int row = 16 * wave + 2 * m + hr;
;         const u32x4 o = *(const LAS u32x4*)(buf + row * TCP + c * 16);
;         asm volatile("global_store_dwordx4 %0, %1, off sc1\n\ts_nop 1" :: "v"(WT + (size_t)row_map(mode, n0 + row) * K + k0 + 8 * c), "v"(o) : "memory"); }
; __global__ void __launch_bounds__(NTHREADS, 2) mega_fwd(Args args) {
;     ...
;         int nbuf = 0;
;         for (int it = bid; it < DEPTH * I_LAYER; it += G, nbuf ^= 1) {
;             const int itr = DEPTH * I_LAYER - 1 - it;
;             const int l = itr / I_LAYER; int r = itr - l * I_LAYER;
.Ldc_pre:
	v_ashrrev_i32_e32 v3, 5, v2
	v_lshl_add_u32 v77, s73, 4, v3
	v_add_u32_e32 v82, 2, v77
	v_lshrrev_b32_e32 v6, 2, v82
	v_and_b32_e32 v84, 16, v6
	v_lshlrev_b32_e32 v6, 2, v82
	v_and_b32_e32 v6, 16, v6
	v_lshrrev_b32_e32 v7, 1, v82
	v_add_u32_e32 v86, 4, v77
	v_and_or_b32 v85, v7, 12, v6
	v_lshrrev_b32_e32 v6, 2, v86
	v_and_b32_e32 v88, 16, v6
	v_lshlrev_b32_e32 v6, 2, v86
	v_and_b32_e32 v6, 16, v6
	v_lshrrev_b32_e32 v7, 1, v86
	v_add_u32_e32 v90, 6, v77
	v_and_or_b32 v89, v7, 12, v6
	v_lshrrev_b32_e32 v6, 2, v90
	v_and_b32_e32 v92, 16, v6
	v_lshlrev_b32_e32 v6, 2, v90
	v_and_b32_e32 v6, 16, v6
	v_lshrrev_b32_e32 v7, 1, v90
	v_add_u32_e32 v97, 10, v77
	v_and_or_b32 v93, v7, 12, v6
	v_lshrrev_b32_e32 v7, 2, v97
	s_add_u32 s36, s12, 0x900000
	v_and_b32_e32 v99, 16, v7
	v_lshlrev_b32_e32 v7, 2, v97
	s_addc_u32 s37, s13, 0
	s_load_dwordx2 s[12:13], s[0:1], 0x8
	s_load_dwordx4 s[4:7], s[0:1], 0x20
	s_load_dwordx4 s[8:11], s[0:1], 0x58
	s_load_dwordx2 s[14:15], s[0:1], 0x30
	s_load_dwordx2 s[16:17], s[0:1], 0x78
	v_and_b32_e32 v7, 16, v7
	v_lshrrev_b32_e32 v8, 1, v97
	v_add_u32_e32 v101, 12, v77
	v_and_or_b32 v100, v8, 12, v7
	v_lshrrev_b32_e32 v7, 2, v101
	v_and_b32_e32 v103, 16, v7
	v_lshlrev_b32_e32 v7, 2, v101
	v_and_b32_e32 v7, 16, v7
	v_lshrrev_b32_e32 v8, 1, v101
	v_add_u32_e32 v105, 14, v77
	s_lshl_b32 s18, s73, 5
	v_add_u32_e32 v94, 8, v77
	v_and_or_b32 v104, v8, 12, v7
	v_lshrrev_b32_e32 v7, 2, v105
	v_and_b32_e32 v4, 31, v2
	v_lshl_add_u32 v66, v3, 4, s18
	v_lshrrev_b32_e32 v5, 2, v77
	v_lshlrev_b32_e32 v3, 2, v3
	v_lshrrev_b32_e32 v6, 2, v94
	v_and_b32_e32 v107, 16, v7
	v_lshlrev_b32_e32 v7, 2, v105
	v_lshlrev_b32_e32 v2, 2, v4
	v_mov_b32_e32 v69, 0
	v_mul_u32_u24_e32 v76, 0x840, v4
	v_lshlrev_b32_e32 v78, 4, v4
	v_lshlrev_b32_e32 v4, 3, v4
	s_movk_i32 s18, 0x210
	v_and_b32_e32 v80, 0x7f, v77
	v_and_b32_e32 v81, 16, v5
	v_and_b32_e32 v3, 16, v3
	v_lshrrev_b32_e32 v5, 1, v77
	v_and_b32_e32 v83, 0x7f, v82
	v_and_b32_e32 v87, 0x7f, v86
	v_and_b32_e32 v91, 0x7f, v90
	v_and_b32_e32 v95, 0x7f, v94
	v_and_b32_e32 v96, 16, v6
	v_lshrrev_b32_e32 v6, 1, v94
	v_and_b32_e32 v98, 0x7f, v97
	v_and_b32_e32 v102, 0x7f, v101
	v_and_b32_e32 v106, 0x7f, v105
	v_and_b32_e32 v7, 16, v7
	v_lshrrev_b32_e32 v8, 1, v105
	v_ashrrev_i32_e32 v67, 31, v66
	v_lshlrev_b32_e32 v75, 1, v66
	v_mul_lo_u32 v79, v77, s18
	v_and_or_b32 v108, v8, 12, v7
	v_or_b32_e32 v109, 0x80, v80
	v_or_b32_e32 v110, 0x80, v83
	v_or_b32_e32 v111, 0x80, v87
	v_or_b32_e32 v112, 0x80, v91
	v_or_b32_e32 v113, 0x80, v95
	v_or_b32_e32 v114, 0x80, v98
	v_or_b32_e32 v115, 0x80, v102
	v_or_b32_e32 v116, 0x80, v106
	v_and_or_b32 v117, v5, 12, v3
	v_and_or_b32 v118, v6, 12, v3
	s_mov_b32 s19, 0
	s_sub_i32 s38, 0, s72
	s_sub_i32 s39, 0x137f, s72
	v_lshlrev_b32_e32 v70, 2, v2
	v_mov_b32_e32 v71, v69
	s_movk_i32 s40, 0xff00
	s_movk_i32 s41, 0xf7ff
	s_movk_i32 s42, 0xffe3
	v_lshlrev_b32_e32 v68, 1, v4
	s_mov_b32 s43, 0
	s_mov_b32 s44, s72
	s_cmp_lg_u32 s98, 0
	s_cbranch_scc1 .Ldc_ovr
	v_readlane_b32 s100, v254, 2
	s_movk_i32 s101, 0x137f
	s_nop 1
	s_mov_b32 s99, s100
	s_cmpk_lg_i32 s100, 0x100
	s_cbranch_scc1 .LBB0_33
	s_cmpk_lt_i32 s72, 0x80
	s_cbranch_scc1 .Ldc_lowhalf
	s_addk_i32 s44, 3424
	s_sub_i32 s38, 0, s44
	s_sub_i32 s39, 0x137f, s44
	s_branch .LBB0_33
.Ldc_lowhalf:
	s_addk_i32 s44, 2496
	s_sub_i32 s38, 0, s44
	s_sub_i32 s39, 0x137f, s44
	s_movk_i32 s100, 1184
	s_branch .LBB0_33

; __global__ void __launch_bounds__(NTHREADS, 2) mega_fwd(Args args) {
;     ...
;         for (int it = bid; it < DEPTH * I_LAYER; it += G, nbuf ^= 1) {
;             const int itr = DEPTH * I_LAYER - 1 - it;
.Ldc_setup:
	v_readlane_b32 s4, v255, 28
	v_readlane_b32 s0, v255, 62
	v_readlane_b32 s1, v255, 63
	v_readlane_b32 s12, v254, 0
	v_readlane_b32 s13, v254, 1
	v_mov_b32_e32 v2, v211
	s_cmp_lg_u32 s4, 0
	s_cselect_b32 s4, 2, 0
	s_and_b32 s5, s98, 3
	s_add_i32 s4, s4, s5
	s_lshr_b32 s5, s98, 2
	s_lshl_b32 s4, s4, 2
	s_or_b32 s4, s4, s5
	s_mov_b32 s99, 1
	s_mov_b32 s101, 0
	s_cmp_eq_u32 s4, 4
	s_cselect_b32 s99, 2400, s99
	s_cselect_b32 s101, 2495, s101
	s_cmp_eq_u32 s4, 5
	s_cselect_b32 s99, 2624, s99
	s_cselect_b32 s101, 3551, s101
	s_cmp_eq_u32 s4, 8
	s_cselect_b32 s99, 0, s99
	s_cselect_b32 s101, 127, s101
	s_cmp_eq_u32 s4, 9
	s_cselect_b32 s99, 1504, s99
	s_cselect_b32 s101, 2399, s101
	s_cmp_eq_u32 s4, 12
	s_cselect_b32 s99, 128, s99
	s_cselect_b32 s101, 383, s101
	s_cmp_eq_u32 s4, 13
	s_cselect_b32 s99, 736, s99
	s_cselect_b32 s101, 1503, s101
	s_cmp_eq_u32 s4, 16
	s_cselect_b32 s99, 384, s99
	s_cselect_b32 s101, 735, s101
	s_cmp_gt_i32 s99, s101
	s_cbranch_scc1 .Ldc_finish
	s_sub_i32 s5, s72, 0x80
	s_add_i32 s99, s99, s5
	s_cmp_gt_i32 s99, s101
	s_cbranch_scc1 .Ldc_nextpass
	s_movk_i32 s100, 0x80
	s_waitcnt lgkmcnt(0)
	s_nop 4
	s_branch .Ldc_pre
